# E24 + P0 prologue pool-map and mem-cache conversion loops issue all 4 iterations of loads up front (8 dwordx4 in flight per thread) when the grid is 256 workgroups
# baseline (speedup 1.0000x reference)
; __device__ __forceinline__ unsigned cvt_pk_bf16(float lo, float hi) { unsigned r; asm volatile("v_cvt_pk_bf16_f32 %0, %1, %2" : "=v"(r) : "v"(lo), "v"(hi)); return r; }
; __device__ __forceinline__ void p0_prologue(const Args& a, LAS unsigned char* lds, int vcu, int G, int tid, int wave, int lane) {
;     ...
;     const int gt = vcu * 512 + tid, NGT = G * 512;
;     for (int i = gt; i < 2 * 4 * 512 * 512 / 4; i += NGT) {
;         const int e = i * 4, l = e >> 20, g = (e >> 18) & 3, dd = e & 511;
;         const f32x4 w = ((const f32x4*)a.in[I_WPOOL])[i] * *(const f32x4*)(a.in[I_PSCALE] + l * PW + g * 512 + dd);
;         u32x2 o; o.x = cvt_pk_bf16(w[0], w[1]); o.y = cvt_pk_bf16(w[2], w[3]);
;         *(u32x2*)(ws + WS_W + (size_t)l * WL_SIZE + WL_P + (size_t)(e & 0xfffff) * 2) = o;
;     }
.LBB0_56:
	v_lshl_add_u32 v10, s33, 9, v1
	s_mov_b32 s0, 0x80000
	s_lshl_b32 s4, s84, 9
	v_cmp_gt_i32_e64 s[0:1], s0, v10
	v_ashrrev_i32_e32 v11, 31, v10
	v_lshlrev_b32_e32 v8, 2, v1
	s_and_saveexec_b64 s[6:7], s[0:1]
	v_readlane_b32 s52, v250, 10
	v_readlane_b32 s62, v250, 20
	v_readlane_b32 s63, v250, 21
	v_readlane_b32 s64, v250, 22
	v_readlane_b32 s65, v250, 23
	v_readlane_b32 s53, v250, 11
	v_readlane_b32 s54, v250, 12
	v_readlane_b32 s55, v250, 13
	v_readlane_b32 s56, v250, 14
	v_readlane_b32 s57, v250, 15
	v_readlane_b32 s58, v250, 16
	v_readlane_b32 s59, v250, 17
	v_readlane_b32 s60, v250, 18
	v_readlane_b32 s61, v250, 19
	v_readlane_b32 s66, v250, 24
	v_readlane_b32 s67, v250, 25
	s_cbranch_execz .LBB0_59
	v_mov_b32_e32 v2, s62
	s_waitcnt lgkmcnt(0)
	v_mov_b32_e32 v3, s63
	v_lshlrev_b32_e32 v1, 3, v1
	s_ashr_i32 s5, s4, 31
	v_lshl_add_u32 v1, s33, 12, v1
	s_lshl_b32 s2, s84, 12
	v_lshl_add_u64 v[2:3], v[10:11], 4, v[2:3]
	s_lshl_b64 s[8:9], s[4:5], 4
	v_lshl_add_u32 v9, s33, 11, v8
	s_lshl_b32 s3, s84, 11
	s_mov_b64 s[10:11], 0
	v_mov_b32_e32 v5, 0
	s_mov_b32 s5, 0x15000000
	v_mov_b64_e32 v[6:7], s[90:91]
	s_mov_b32 s12, 0x7ffff
	v_mov_b32_e32 v12, v10
	s_cmp_lg_u32 s4, 0x20000
	s_cbranch_scc1 .LBB0_58
	v_mov_b32_e32 v78, v1
	v_mov_b32_e32 v79, v12
	v_ashrrev_i32_e32 v13, 18, v12
	v_lshlrev_b32_e32 v60, 11, v13
	v_lshrrev_b32_e32 v4, 5, v12
	v_ashrrev_i32_e32 v61, 31, v60
	v_and_b32_e32 v62, 0x1fc, v9
	v_and_b32_e32 v4, 0x1800, v4
	v_lshl_add_u64 v[60:61], v[60:61], 2, s[64:65]
	v_lshl_add_u64 v[60:61], v[60:61], 0, v[4:5]
	v_lshlrev_b32_e32 v4, 2, v62
	v_lshl_add_u64 v[60:61], v[60:61], 0, v[4:5]
	global_load_dwordx4 v[14:17], v[2:3], off
	global_load_dwordx4 v[18:21], v[60:61], off
	v_add_u32_e32 v12, s4, v12
	v_add_u32_e32 v9, s3, v9
	v_lshl_add_u64 v[2:3], v[2:3], 0, s[8:9]
	v_ashrrev_i32_e32 v13, 18, v12
	v_lshlrev_b32_e32 v60, 11, v13
	v_lshrrev_b32_e32 v4, 5, v12
	v_ashrrev_i32_e32 v61, 31, v60
	v_and_b32_e32 v62, 0x1fc, v9
	v_and_b32_e32 v4, 0x1800, v4
	v_lshl_add_u64 v[60:61], v[60:61], 2, s[64:65]
	v_lshl_add_u64 v[60:61], v[60:61], 0, v[4:5]
	v_lshlrev_b32_e32 v4, 2, v62
	v_lshl_add_u64 v[60:61], v[60:61], 0, v[4:5]
	global_load_dwordx4 v[48:51], v[2:3], off
	global_load_dwordx4 v[70:73], v[60:61], off
	v_add_u32_e32 v12, s4, v12
	v_add_u32_e32 v9, s3, v9
	v_lshl_add_u64 v[2:3], v[2:3], 0, s[8:9]
	v_ashrrev_i32_e32 v13, 18, v12
	v_lshlrev_b32_e32 v60, 11, v13
	v_lshrrev_b32_e32 v4, 5, v12
	v_ashrrev_i32_e32 v61, 31, v60
	v_and_b32_e32 v62, 0x1fc, v9
	v_and_b32_e32 v4, 0x1800, v4
	v_lshl_add_u64 v[60:61], v[60:61], 2, s[64:65]
	v_lshl_add_u64 v[60:61], v[60:61], 0, v[4:5]
	v_lshlrev_b32_e32 v4, 2, v62
	v_lshl_add_u64 v[60:61], v[60:61], 0, v[4:5]
	global_load_dwordx4 v[52:55], v[2:3], off
	global_load_dwordx4 v[74:77], v[60:61], off
	v_add_u32_e32 v12, s4, v12
	v_add_u32_e32 v9, s3, v9
	v_lshl_add_u64 v[2:3], v[2:3], 0, s[8:9]
	v_ashrrev_i32_e32 v13, 18, v12
	v_lshlrev_b32_e32 v60, 11, v13
	v_lshrrev_b32_e32 v4, 5, v12
	v_ashrrev_i32_e32 v61, 31, v60
	v_and_b32_e32 v62, 0x1fc, v9
	v_and_b32_e32 v4, 0x1800, v4
	v_lshl_add_u64 v[60:61], v[60:61], 2, s[64:65]
	v_lshl_add_u64 v[60:61], v[60:61], 0, v[4:5]
	v_lshlrev_b32_e32 v4, 2, v62
	v_lshl_add_u64 v[60:61], v[60:61], 0, v[4:5]
	global_load_dwordx4 v[56:59], v[2:3], off
	global_load_dwordx4 v[22:25], v[60:61], off
	v_add_u32_e32 v12, s4, v12
	v_add_u32_e32 v9, s3, v9
	v_lshl_add_u64 v[2:3], v[2:3], 0, s[8:9]
	v_ashrrev_i32_e32 v13, 18, v79
	v_mad_i64_i32 v[60:61], s[14:15], v13, s5, v[6:7]
	v_and_b32_e32 v4, 0x1ffff8, v78
	v_lshl_add_u64 v[60:61], v[60:61], 0, v[4:5]
	v_add_co_u32_e32 v60, vcc, 0x2600000, v60
	v_add_u32_e32 v79, s4, v79
	v_add_u32_e32 v78, s2, v78
	v_addc_co_u32_e32 v61, vcc, 0, v61, vcc
	s_waitcnt vmcnt(6)
	v_pk_mul_f32 v[14:15], v[14:15], v[18:19]
	v_pk_mul_f32 v[16:17], v[16:17], v[20:21]
	v_cvt_pk_bf16_f32 v14, v14, v15
	s_nop 0
	v_cvt_pk_bf16_f32 v15, v16, v17
	global_store_dwordx2 v[60:61], v[14:15], off
	v_ashrrev_i32_e32 v13, 18, v79
	v_mad_i64_i32 v[60:61], s[14:15], v13, s5, v[6:7]
	v_and_b32_e32 v4, 0x1ffff8, v78
	v_lshl_add_u64 v[60:61], v[60:61], 0, v[4:5]
	v_add_co_u32_e32 v60, vcc, 0x2600000, v60
	v_add_u32_e32 v79, s4, v79
	v_add_u32_e32 v78, s2, v78
	v_addc_co_u32_e32 v61, vcc, 0, v61, vcc
	s_waitcnt vmcnt(5)
	v_pk_mul_f32 v[48:49], v[48:49], v[70:71]
	v_pk_mul_f32 v[50:51], v[50:51], v[72:73]
	v_cvt_pk_bf16_f32 v48, v48, v49
	s_nop 0
	v_cvt_pk_bf16_f32 v49, v50, v51
	global_store_dwordx2 v[60:61], v[48:49], off
	v_ashrrev_i32_e32 v13, 18, v79
	v_mad_i64_i32 v[60:61], s[14:15], v13, s5, v[6:7]
	v_and_b32_e32 v4, 0x1ffff8, v78
	v_lshl_add_u64 v[60:61], v[60:61], 0, v[4:5]
	v_add_co_u32_e32 v60, vcc, 0x2600000, v60
	v_add_u32_e32 v79, s4, v79
	v_add_u32_e32 v78, s2, v78
	v_addc_co_u32_e32 v61, vcc, 0, v61, vcc
	s_waitcnt vmcnt(4)
	v_pk_mul_f32 v[52:53], v[52:53], v[74:75]
	v_pk_mul_f32 v[54:55], v[54:55], v[76:77]
	v_cvt_pk_bf16_f32 v52, v52, v53
	s_nop 0
	v_cvt_pk_bf16_f32 v53, v54, v55
	global_store_dwordx2 v[60:61], v[52:53], off
	v_ashrrev_i32_e32 v13, 18, v79
	v_mad_i64_i32 v[60:61], s[14:15], v13, s5, v[6:7]
	v_and_b32_e32 v4, 0x1ffff8, v78
	v_lshl_add_u64 v[60:61], v[60:61], 0, v[4:5]
	v_add_co_u32_e32 v60, vcc, 0x2600000, v60
	v_add_u32_e32 v79, s4, v79
	v_add_u32_e32 v78, s2, v78
	v_addc_co_u32_e32 v61, vcc, 0, v61, vcc
	s_waitcnt vmcnt(3)
	v_pk_mul_f32 v[56:57], v[56:57], v[22:23]
	v_pk_mul_f32 v[58:59], v[58:59], v[24:25]
	v_cvt_pk_bf16_f32 v56, v56, v57
	s_nop 0
	v_cvt_pk_bf16_f32 v57, v58, v59
	global_store_dwordx2 v[60:61], v[56:57], off
	v_mov_b32_e32 v1, v78
	s_branch .LBB0_59

; __device__ __forceinline__ unsigned cvt_pk_bf16(float lo, float hi) { unsigned r; asm volatile("v_cvt_pk_bf16_f32 %0, %1, %2" : "=v"(r) : "v"(lo), "v"(hi)); return r; }
; __device__ __forceinline__ void p0_prologue(const Args& a, LAS unsigned char* lds, int vcu, int G, int tid, int wave, int lane) {
;     ...
;     for (int i = gt; i < 2 * 8 * 256 * 512 / 4; i += NGT) {
;         const f32x4 kv = ((const f32x4*)a.in[I_CMK])[i], vv = ((const f32x4*)a.in[I_CMV])[i];
;         u32x2 w; w.x = cvt_pk_bf16(kv[0], kv[1]); w.y = cvt_pk_bf16(kv[2], kv[3]); ((u32x2*)(ws + WS_MKS))[i] = w;
;         w.x = cvt_pk_bf16(vv[0], vv[1]); w.y = cvt_pk_bf16(vv[2], vv[3]); ((u32x2*)(ws + WS_MVS))[i] = w;
;     }
.LBB0_64:
	s_or_b64 exec, exec, s[6:7]
	s_and_saveexec_b64 s[6:7], s[0:1]
	v_readlane_b32 s56, v250, 28
	v_readlane_b32 s64, v250, 36
	v_readlane_b32 s65, v250, 37
	v_readlane_b32 s66, v250, 38
	v_readlane_b32 s67, v250, 39
	v_readlane_b32 s68, v250, 40
	v_readlane_b32 s69, v250, 41
	v_readlane_b32 s57, v250, 29
	v_readlane_b32 s58, v250, 30
	v_readlane_b32 s59, v250, 31
	v_readlane_b32 s60, v250, 32
	v_readlane_b32 s61, v250, 33
	v_readlane_b32 s62, v250, 34
	v_readlane_b32 s63, v250, 35
	v_readlane_b32 s70, v250, 42
	v_readlane_b32 s71, v250, 43
	s_cbranch_execz .LBB0_67
	s_mov_b64 s[12:13], s[64:65]
	s_ashr_i32 s5, s4, 31
	v_lshl_add_u64 v[4:5], v[10:11], 3, s[90:91]
	s_mov_b64 s[2:3], 0x4a300000
	s_mov_b64 s[14:15], s[66:67]
	s_mov_b64 s[16:17], s[68:69]
	s_waitcnt lgkmcnt(0)
	v_lshlrev_b64 v[2:3], 4, v[10:11]
	s_lshl_b64 s[0:1], s[4:5], 4
	v_lshl_add_u64 v[4:5], v[4:5], 0, s[2:3]
	s_lshl_b64 s[8:9], s[4:5], 3
	s_mov_b64 s[10:11], 0
	s_mov_b32 s2, 0x7ffff
	s_cmp_lg_u32 s4, 0x20000
	s_cbranch_scc1 .LBB0_66
	v_lshl_add_u64 v[16:17], s[14:15], 0, v[2:3]
	v_lshl_add_u64 v[74:75], s[16:17], 0, v[2:3]
	global_load_dwordx4 v[6:9], v[16:17], off
	global_load_dwordx4 v[12:15], v[74:75], off
	v_lshl_add_u64 v[16:17], v[16:17], 0, s[0:1]
	v_lshl_add_u64 v[74:75], v[74:75], 0, s[0:1]
	global_load_dwordx4 v[18:21], v[16:17], off
	global_load_dwordx4 v[22:25], v[74:75], off
	v_lshl_add_u64 v[16:17], v[16:17], 0, s[0:1]
	v_lshl_add_u64 v[74:75], v[74:75], 0, s[0:1]
	global_load_dwordx4 v[48:51], v[16:17], off
	global_load_dwordx4 v[52:55], v[74:75], off
	v_lshl_add_u64 v[16:17], v[16:17], 0, s[0:1]
	v_lshl_add_u64 v[74:75], v[74:75], 0, s[0:1]
	global_load_dwordx4 v[56:59], v[16:17], off
	global_load_dwordx4 v[70:73], v[74:75], off
	v_add_co_u32_e32 v16, vcc, 0x400000, v4
	s_nop 1
	v_addc_co_u32_e32 v17, vcc, 0, v5, vcc
	s_waitcnt vmcnt(7)
	v_cvt_pk_bf16_f32 v6, v6, v7
	v_cvt_pk_bf16_f32 v7, v8, v9
	global_store_dwordx2 v[4:5], v[6:7], off
	v_lshl_add_u64 v[4:5], v[4:5], 0, s[8:9]
	s_waitcnt vmcnt(7)
	v_cvt_pk_bf16_f32 v12, v12, v13
	v_cvt_pk_bf16_f32 v13, v14, v15
	global_store_dwordx2 v[16:17], v[12:13], off
	v_add_co_u32_e32 v16, vcc, 0x400000, v4
	s_nop 1
	v_addc_co_u32_e32 v17, vcc, 0, v5, vcc
	s_waitcnt vmcnt(7)
	v_cvt_pk_bf16_f32 v18, v18, v19
	v_cvt_pk_bf16_f32 v19, v20, v21
	global_store_dwordx2 v[4:5], v[18:19], off
	v_lshl_add_u64 v[4:5], v[4:5], 0, s[8:9]
	s_waitcnt vmcnt(7)
	v_cvt_pk_bf16_f32 v22, v22, v23
	v_cvt_pk_bf16_f32 v23, v24, v25
	global_store_dwordx2 v[16:17], v[22:23], off
	v_add_co_u32_e32 v16, vcc, 0x400000, v4
	s_nop 1
	v_addc_co_u32_e32 v17, vcc, 0, v5, vcc
	s_waitcnt vmcnt(7)
	v_cvt_pk_bf16_f32 v48, v48, v49
	v_cvt_pk_bf16_f32 v49, v50, v51
	global_store_dwordx2 v[4:5], v[48:49], off
	v_lshl_add_u64 v[4:5], v[4:5], 0, s[8:9]
	s_waitcnt vmcnt(7)
	v_cvt_pk_bf16_f32 v52, v52, v53
	v_cvt_pk_bf16_f32 v53, v54, v55
	global_store_dwordx2 v[16:17], v[52:53], off
	v_add_co_u32_e32 v16, vcc, 0x400000, v4
	s_nop 1
	v_addc_co_u32_e32 v17, vcc, 0, v5, vcc
	s_waitcnt vmcnt(7)
	v_cvt_pk_bf16_f32 v56, v56, v57
	v_cvt_pk_bf16_f32 v57, v58, v59
	global_store_dwordx2 v[4:5], v[56:57], off
	v_lshl_add_u64 v[4:5], v[4:5], 0, s[8:9]
	s_waitcnt vmcnt(7)
	v_cvt_pk_bf16_f32 v70, v70, v71
	v_cvt_pk_bf16_f32 v71, v72, v73
	global_store_dwordx2 v[16:17], v[70:71], off
	v_lshl_add_u32 v10, s4, 2, v10
	s_branch .LBB0_67
